# lever 9: SB all-waves-done test shortened (7 serial v_add_u32 -> v_add3_u32 tree of depth 3)
# baseline (speedup 1.0000x reference)
; #define LAS __attribute__((address_space(3)))
; __device__ __forceinline__ void p_attn_sb(const Params& P, LAS unsigned char* lds) {
;     ...
;             if (wdone && lane == 0) flags[(j & 1) * 8 + w] = 1;
;             if (more) { *(LAS u32x4*)(lds + A_K + ((j + 1) & 1) * TILE_B + srow * KP + sch * 16) = kreg; *(LAS u32x4*)(lds + A_V + ((j + 1) & 1) * TILE_B + srow * KP + sch * 16) = vreg; }
;             __syncthreads();
;             const u32x4 fa_ = *(const LAS u32x4*)(flags + (j & 1) * 8), fb_ = *(const LAS u32x4*)(flags + (j & 1) * 8 + 4);
;             if ((fa_.x + fa_.y + fa_.z + fa_.w) + (fb_.x + fb_.y + fb_.z + fb_.w) == 8u) break;
.LBB0_409:
	s_lshl_b32 s12, s41, 5
	s_add_i32 s12, s12, 0
	v_mov_b32_e32 v1, s12
	s_waitcnt lgkmcnt(0)
	s_barrier
	ds_read_b128 v[2:5], v1 offset:40192
	ds_read_b128 v[6:9], v1 offset:40208
	s_sub_i32 s25, s25, 64
	s_add_i32 s29, s29, -2
	s_add_i32 s28, s28, -1
	s_waitcnt lgkmcnt(1)
	v_add3_u32 v1, v2, v3, v4
	s_waitcnt lgkmcnt(0)
	v_add3_u32 v2, v5, v6, v7
	v_add3_u32 v1, v1, v8, v9
	v_add_u32_e32 v1, v1, v2
	v_cmp_eq_u32_e64 s[14:15], 8, v1
	s_add_i32 s33, s33, 1
	s_and_b64 vcc, exec, s[14:15]
	s_cbranch_vccz .LBB0_399
	s_branch .LBB0_394
